# resid+norm epilogue part 2 rewritten too: one load batch after the grid barrier, stores streamed without vmcnt waits
# speedup vs baseline: 1.0409x; 1.0001x over previous
.LBB0_532:
	v_and_b32_e32 v130, 64, v209
	s_lshl_b32 s6, s81, 8
	v_xor_b32_e32 v0, 16, v209
	v_add_u32_e32 v130, 64, v130
	s_add_i32 s6, s6, s47
	v_cmp_lt_i32_e32 vcc, v0, v130
	v_xor_b32_e32 v131, 32, v209
	s_lshl_b32 s0, s34, 5
	v_add_u32_e32 v194, s6, v145
	s_lshl_b32 s6, s84, 8
	v_cndmask_b32_e32 v0, v209, v0, vcc
	v_cmp_lt_i32_e32 vcc, v131, v130
	s_or_b32 s0, s6, s0
	v_ashrrev_i32_e32 v195, 31, v194
	v_cndmask_b32_e32 v130, v209, v131, vcc
	v_lshl_or_b32 v166, v144, 3, s0
	v_lshlrev_b32_e32 v172, 2, v130
	v_lshlrev_b64 v[130:131], 12, v[194:195]
	v_ashrrev_i32_e32 v167, 31, v166
	v_lshl_add_u64 v[130:131], s[16:17], 0, v[130:131]
	v_lshl_add_u64 v[138:139], v[166:167], 2, v[130:131]
	s_barrier
	v_lshlrev_b32_e32 v0, 2, v0
	v_mov_b32_e32 v251, v172
	v_cmp_eq_u32_e32 vcc, 0, v144
	v_lshlrev_b32_e32 v200, 12, v194
	v_lshl_add_u32 v200, v166, 2, v200
	s_mov_b64 s[100:101], s[16:17]
	global_load_dwordx4 v[150:153], v200, s[100:101]
	global_load_dwordx4 v[146:149], v200, s[100:101] offset:16
	global_load_dwordx4 v[154:157], v200, s[100:101] offset:512
	global_load_dwordx4 v[158:161], v200, s[100:101] offset:528
	s_add_u32 s100, s16, 0x10000
	s_addc_u32 s101, s17, 0
	global_load_dwordx4 v[134:137], v200, s[100:101]
	global_load_dwordx4 v[130:133], v200, s[100:101] offset:16
	global_load_dwordx4 v[138:141], v200, s[100:101] offset:512
	global_load_dwordx4 v[142:145], v200, s[100:101] offset:528
	s_add_u32 s100, s16, 0x20000
	s_addc_u32 s101, s17, 0
	global_load_dwordx4 v[210:213], v200, s[100:101]
	global_load_dwordx4 v[214:217], v200, s[100:101] offset:16
	global_load_dwordx4 v[218:221], v200, s[100:101] offset:512
	global_load_dwordx4 v[222:225], v200, s[100:101] offset:528
	s_add_u32 s100, s16, 0x30000
	s_addc_u32 s101, s17, 0
	global_load_dwordx4 v[226:229], v200, s[100:101]
	global_load_dwordx4 v[230:233], v200, s[100:101] offset:16
	global_load_dwordx4 v[234:237], v200, s[100:101] offset:512
	global_load_dwordx4 v[238:241], v200, s[100:101] offset:528
	s_lshl_b32 s6, s84, 2
	s_ashr_i32 s7, s6, 31
	s_lshl_b64 s[6:7], s[6:7], 2
	s_add_u32 s0, s22, s6
	s_addc_u32 s7, s23, s7
	s_lshl_b32 s6, s34, 2
	s_add_u32 s6, s0, s6
	s_addc_u32 s7, s7, 0
	v_readlane_b32 s28, v254, 39
	s_mov_b32 s98, s36
	s_mov_b32 s83, 0x800000
	v_readlane_b32 s29, v254, 40
	v_readlane_b32 s48, v254, 41
	s_mov_b64 s[34:35], s[50:51]
	v_readlane_b32 s49, v254, 42
	s_waitcnt vmcnt(12)
	v_pk_fma_f32 v[150:151], s[18:19], v[126:127], v[150:151]
	v_pk_fma_f32 v[152:153], s[24:25], v[128:129], v[152:153]
	v_pk_fma_f32 v[146:147], s[18:19], v[122:123], v[146:147]
	v_pk_fma_f32 v[148:149], s[24:25], v[124:125], v[148:149]
	v_pk_fma_f32 v[154:155], s[18:19], v[118:119], v[154:155]
	v_pk_fma_f32 v[156:157], s[24:25], v[120:121], v[156:157]
	v_pk_fma_f32 v[158:159], s[18:19], v[114:115], v[158:159]
	v_pk_fma_f32 v[160:161], s[24:25], v[116:117], v[160:161]
	v_mul_f32_e32 v202, v153, v153
	v_mul_f32_e32 v201, v151, v151
	v_fmac_f32_e32 v201, v150, v150
	v_fmac_f32_e32 v202, v152, v152
	v_add_f32_e32 v201, v201, v202
	v_mul_f32_e32 v206, v149, v149
	v_mul_f32_e32 v203, v147, v147
	v_fmac_f32_e32 v203, v146, v146
	v_fmac_f32_e32 v206, v148, v148
	v_add_f32_e32 v203, v203, v206
	v_add_f32_e32 v201, v201, v203
	v_mul_f32_e32 v206, v157, v157
	v_mul_f32_e32 v203, v155, v155
	v_fmac_f32_e32 v203, v154, v154
	v_fmac_f32_e32 v206, v156, v156
	v_add_f32_e32 v203, v203, v206
	v_mul_f32_e32 v206, v161, v161
	v_mul_f32_e32 v202, v159, v159
	v_fmac_f32_e32 v202, v158, v158
	v_fmac_f32_e32 v206, v160, v160
	v_add_f32_e32 v202, v202, v206
	v_add_f32_e32 v203, v203, v202
	v_add_f32_e32 v242, v201, v203
	s_add_u32 s100, s16, 0x80000
	s_addc_u32 s101, s17, 0
	global_load_dwordx4 v[114:117], v200, s[100:101]
	global_load_dwordx4 v[118:121], v200, s[100:101] offset:16
	global_load_dwordx4 v[122:125], v200, s[100:101] offset:512
	global_load_dwordx4 v[126:129], v200, s[100:101] offset:528
	s_waitcnt vmcnt(12)
	v_pk_fma_f32 v[134:135], s[18:19], v[110:111], v[134:135]
	v_pk_fma_f32 v[136:137], s[24:25], v[112:113], v[136:137]
	v_pk_fma_f32 v[130:131], s[18:19], v[106:107], v[130:131]
	v_pk_fma_f32 v[132:133], s[24:25], v[108:109], v[132:133]
	v_pk_fma_f32 v[138:139], s[18:19], v[102:103], v[138:139]
	v_pk_fma_f32 v[140:141], s[24:25], v[104:105], v[140:141]
	v_pk_fma_f32 v[142:143], s[18:19], v[98:99], v[142:143]
	v_pk_fma_f32 v[144:145], s[24:25], v[100:101], v[144:145]
	v_mul_f32_e32 v202, v137, v137
	v_mul_f32_e32 v201, v135, v135
	v_fmac_f32_e32 v201, v134, v134
	v_fmac_f32_e32 v202, v136, v136
	v_add_f32_e32 v201, v201, v202
	v_mul_f32_e32 v206, v133, v133
	v_mul_f32_e32 v203, v131, v131
	v_fmac_f32_e32 v203, v130, v130
	v_fmac_f32_e32 v206, v132, v132
	v_add_f32_e32 v203, v203, v206
	v_add_f32_e32 v201, v201, v203
	v_mul_f32_e32 v206, v141, v141
	v_mul_f32_e32 v203, v139, v139
	v_fmac_f32_e32 v203, v138, v138
	v_fmac_f32_e32 v206, v140, v140
	v_add_f32_e32 v203, v203, v206
	v_mul_f32_e32 v206, v145, v145
	v_mul_f32_e32 v202, v143, v143
	v_fmac_f32_e32 v202, v142, v142
	v_fmac_f32_e32 v206, v144, v144
	v_add_f32_e32 v202, v202, v206
	v_add_f32_e32 v203, v203, v202
	v_add_f32_e32 v243, v201, v203
	s_add_u32 s100, s16, 0x90000
	s_addc_u32 s101, s17, 0
	global_load_dwordx4 v[98:101], v200, s[100:101]
	global_load_dwordx4 v[102:105], v200, s[100:101] offset:16
	global_load_dwordx4 v[106:109], v200, s[100:101] offset:512
	global_load_dwordx4 v[110:113], v200, s[100:101] offset:528
	s_waitcnt vmcnt(12)
	v_pk_fma_f32 v[86:87], s[18:19], v[86:87], v[210:211]
	v_pk_fma_f32 v[88:89], s[24:25], v[88:89], v[212:213]
	v_pk_fma_f32 v[82:83], s[18:19], v[82:83], v[214:215]
	v_pk_fma_f32 v[84:85], s[24:25], v[84:85], v[216:217]
	v_pk_fma_f32 v[90:91], s[18:19], v[90:91], v[218:219]
	v_pk_fma_f32 v[92:93], s[24:25], v[92:93], v[220:221]
	v_pk_fma_f32 v[94:95], s[18:19], v[94:95], v[222:223]
	v_pk_fma_f32 v[96:97], s[24:25], v[96:97], v[224:225]
	v_mul_f32_e32 v202, v89, v89
	v_mul_f32_e32 v201, v87, v87
	v_fmac_f32_e32 v201, v86, v86
	v_fmac_f32_e32 v202, v88, v88
	v_add_f32_e32 v201, v201, v202
	v_mul_f32_e32 v206, v85, v85
	v_mul_f32_e32 v203, v83, v83
	v_fmac_f32_e32 v203, v82, v82
	v_fmac_f32_e32 v206, v84, v84
	v_add_f32_e32 v203, v203, v206
	v_add_f32_e32 v201, v201, v203
	v_mul_f32_e32 v206, v93, v93
	v_mul_f32_e32 v203, v91, v91
	v_fmac_f32_e32 v203, v90, v90
	v_fmac_f32_e32 v206, v92, v92
	v_add_f32_e32 v203, v203, v206
	v_mul_f32_e32 v206, v97, v97
	v_mul_f32_e32 v202, v95, v95
	v_fmac_f32_e32 v202, v94, v94
	v_fmac_f32_e32 v206, v96, v96
	v_add_f32_e32 v202, v202, v206
	v_add_f32_e32 v203, v203, v202
	v_add_f32_e32 v244, v201, v203
	s_add_u32 s100, s16, 0xa0000
	s_addc_u32 s101, s17, 0
	global_load_dwordx4 v[210:213], v200, s[100:101]
	global_load_dwordx4 v[214:217], v200, s[100:101] offset:16
	global_load_dwordx4 v[218:221], v200, s[100:101] offset:512
	global_load_dwordx4 v[222:225], v200, s[100:101] offset:528
	s_waitcnt vmcnt(12)
	v_pk_fma_f32 v[70:71], s[18:19], v[70:71], v[226:227]
	v_pk_fma_f32 v[72:73], s[24:25], v[72:73], v[228:229]
	v_pk_fma_f32 v[66:67], s[18:19], v[66:67], v[230:231]
	v_pk_fma_f32 v[68:69], s[24:25], v[68:69], v[232:233]
	v_pk_fma_f32 v[74:75], s[18:19], v[74:75], v[234:235]
	v_pk_fma_f32 v[76:77], s[24:25], v[76:77], v[236:237]
	v_pk_fma_f32 v[78:79], s[18:19], v[78:79], v[238:239]
	v_pk_fma_f32 v[80:81], s[24:25], v[80:81], v[240:241]
	v_mul_f32_e32 v202, v73, v73
	v_mul_f32_e32 v201, v71, v71
	v_fmac_f32_e32 v201, v70, v70
	v_fmac_f32_e32 v202, v72, v72
	v_add_f32_e32 v201, v201, v202
	v_mul_f32_e32 v206, v69, v69
	v_mul_f32_e32 v203, v67, v67
	v_fmac_f32_e32 v203, v66, v66
	v_fmac_f32_e32 v206, v68, v68
	v_add_f32_e32 v203, v203, v206
	v_add_f32_e32 v201, v201, v203
	v_mul_f32_e32 v206, v77, v77
	v_mul_f32_e32 v203, v75, v75
	v_fmac_f32_e32 v203, v74, v74
	v_fmac_f32_e32 v206, v76, v76
	v_add_f32_e32 v203, v203, v206
	v_mul_f32_e32 v206, v81, v81
	v_mul_f32_e32 v202, v79, v79
	v_fmac_f32_e32 v202, v78, v78
	v_fmac_f32_e32 v206, v80, v80
	v_add_f32_e32 v202, v202, v206
	v_add_f32_e32 v203, v203, v202
	v_add_f32_e32 v245, v201, v203
	s_add_u32 s100, s16, 0xb0000
	s_addc_u32 s101, s17, 0
	global_load_dwordx4 v[226:229], v200, s[100:101]
	global_load_dwordx4 v[230:233], v200, s[100:101] offset:16
	global_load_dwordx4 v[234:237], v200, s[100:101] offset:512
	global_load_dwordx4 v[238:241], v200, s[100:101] offset:528
	s_waitcnt vmcnt(12)
	v_pk_fma_f32 v[54:55], s[18:19], v[54:55], v[114:115]
	v_pk_fma_f32 v[56:57], s[24:25], v[56:57], v[116:117]
	v_pk_fma_f32 v[50:51], s[18:19], v[50:51], v[118:119]
	v_pk_fma_f32 v[52:53], s[24:25], v[52:53], v[120:121]
	v_pk_fma_f32 v[58:59], s[18:19], v[58:59], v[122:123]
	v_pk_fma_f32 v[60:61], s[24:25], v[60:61], v[124:125]
	v_pk_fma_f32 v[62:63], s[18:19], v[62:63], v[126:127]
	v_pk_fma_f32 v[64:65], s[24:25], v[64:65], v[128:129]
	v_mul_f32_e32 v202, v57, v57
	v_mul_f32_e32 v201, v55, v55
	v_fmac_f32_e32 v201, v54, v54
	v_fmac_f32_e32 v202, v56, v56
	v_add_f32_e32 v201, v201, v202
	v_mul_f32_e32 v206, v53, v53
	v_mul_f32_e32 v203, v51, v51
	v_fmac_f32_e32 v203, v50, v50
	v_fmac_f32_e32 v206, v52, v52
	v_add_f32_e32 v203, v203, v206
	v_add_f32_e32 v201, v201, v203
	v_mul_f32_e32 v206, v61, v61
	v_mul_f32_e32 v203, v59, v59
	v_fmac_f32_e32 v203, v58, v58
	v_fmac_f32_e32 v206, v60, v60
	v_add_f32_e32 v203, v203, v206
	v_mul_f32_e32 v206, v65, v65
	v_mul_f32_e32 v202, v63, v63
	v_fmac_f32_e32 v202, v62, v62
	v_fmac_f32_e32 v206, v64, v64
	v_add_f32_e32 v202, v202, v206
	v_add_f32_e32 v203, v203, v202
	v_add_f32_e32 v246, v201, v203
	s_waitcnt vmcnt(8)
	v_pk_fma_f32 v[38:39], s[18:19], v[38:39], v[98:99]
	v_pk_fma_f32 v[40:41], s[24:25], v[40:41], v[100:101]
	v_pk_fma_f32 v[34:35], s[18:19], v[34:35], v[102:103]
	v_pk_fma_f32 v[36:37], s[24:25], v[36:37], v[104:105]
	v_pk_fma_f32 v[42:43], s[18:19], v[42:43], v[106:107]
	v_pk_fma_f32 v[44:45], s[24:25], v[44:45], v[108:109]
	v_pk_fma_f32 v[46:47], s[18:19], v[46:47], v[110:111]
	v_pk_fma_f32 v[48:49], s[24:25], v[48:49], v[112:113]
	v_mul_f32_e32 v202, v41, v41
	v_mul_f32_e32 v201, v39, v39
	v_fmac_f32_e32 v201, v38, v38
	v_fmac_f32_e32 v202, v40, v40
	v_add_f32_e32 v201, v201, v202
	v_mul_f32_e32 v206, v37, v37
	v_mul_f32_e32 v203, v35, v35
	v_fmac_f32_e32 v203, v34, v34
	v_fmac_f32_e32 v206, v36, v36
	v_add_f32_e32 v203, v203, v206
	v_add_f32_e32 v201, v201, v203
	v_mul_f32_e32 v206, v45, v45
	v_mul_f32_e32 v203, v43, v43
	v_fmac_f32_e32 v203, v42, v42
	v_fmac_f32_e32 v206, v44, v44
	v_add_f32_e32 v203, v203, v206
	v_mul_f32_e32 v206, v49, v49
	v_mul_f32_e32 v202, v47, v47
	v_fmac_f32_e32 v202, v46, v46
	v_fmac_f32_e32 v206, v48, v48
	v_add_f32_e32 v202, v202, v206
	v_add_f32_e32 v203, v203, v202
	v_add_f32_e32 v247, v201, v203
	s_waitcnt vmcnt(4)
	v_pk_fma_f32 v[22:23], s[18:19], v[22:23], v[210:211]
	v_pk_fma_f32 v[24:25], s[24:25], v[24:25], v[212:213]
	v_pk_fma_f32 v[18:19], s[18:19], v[18:19], v[214:215]
	v_pk_fma_f32 v[20:21], s[24:25], v[20:21], v[216:217]
	v_pk_fma_f32 v[26:27], s[18:19], v[26:27], v[218:219]
	v_pk_fma_f32 v[28:29], s[24:25], v[28:29], v[220:221]
	v_pk_fma_f32 v[30:31], s[18:19], v[30:31], v[222:223]
	v_pk_fma_f32 v[32:33], s[24:25], v[32:33], v[224:225]
	v_mul_f32_e32 v202, v25, v25
	v_mul_f32_e32 v201, v23, v23
	v_fmac_f32_e32 v201, v22, v22
	v_fmac_f32_e32 v202, v24, v24
	v_add_f32_e32 v201, v201, v202
	v_mul_f32_e32 v206, v21, v21
	v_mul_f32_e32 v203, v19, v19
	v_fmac_f32_e32 v203, v18, v18
	v_fmac_f32_e32 v206, v20, v20
	v_add_f32_e32 v203, v203, v206
	v_add_f32_e32 v201, v201, v203
	v_mul_f32_e32 v206, v29, v29
	v_mul_f32_e32 v203, v27, v27
	v_fmac_f32_e32 v203, v26, v26
	v_fmac_f32_e32 v206, v28, v28
	v_add_f32_e32 v203, v203, v206
	v_mul_f32_e32 v206, v33, v33
	v_mul_f32_e32 v202, v31, v31
	v_fmac_f32_e32 v202, v30, v30
	v_fmac_f32_e32 v206, v32, v32
	v_add_f32_e32 v202, v202, v206
	v_add_f32_e32 v203, v203, v202
	v_add_f32_e32 v248, v201, v203
	s_waitcnt vmcnt(0)
	v_pk_fma_f32 v[6:7], s[18:19], v[6:7], v[226:227]
	v_pk_fma_f32 v[8:9], s[24:25], v[8:9], v[228:229]
	v_pk_fma_f32 v[2:3], s[18:19], v[2:3], v[230:231]
	v_pk_fma_f32 v[4:5], s[24:25], v[4:5], v[232:233]
	v_pk_fma_f32 v[10:11], s[18:19], v[10:11], v[234:235]
	v_pk_fma_f32 v[12:13], s[24:25], v[12:13], v[236:237]
	v_pk_fma_f32 v[14:15], s[18:19], v[14:15], v[238:239]
	v_pk_fma_f32 v[16:17], s[24:25], v[16:17], v[240:241]
	v_mul_f32_e32 v202, v9, v9
	v_mul_f32_e32 v201, v7, v7
	v_fmac_f32_e32 v201, v6, v6
	v_fmac_f32_e32 v202, v8, v8
	v_add_f32_e32 v201, v201, v202
	v_mul_f32_e32 v206, v5, v5
	v_mul_f32_e32 v203, v3, v3
	v_fmac_f32_e32 v203, v2, v2
	v_fmac_f32_e32 v206, v4, v4
	v_add_f32_e32 v203, v203, v206
	v_add_f32_e32 v201, v201, v203
	v_mul_f32_e32 v206, v13, v13
	v_mul_f32_e32 v203, v11, v11
	v_fmac_f32_e32 v203, v10, v10
	v_fmac_f32_e32 v206, v12, v12
	v_add_f32_e32 v203, v203, v206
	v_mul_f32_e32 v206, v17, v17
	v_mul_f32_e32 v202, v15, v15
	v_fmac_f32_e32 v202, v14, v14
	v_fmac_f32_e32 v206, v16, v16
	v_add_f32_e32 v202, v202, v206
	v_add_f32_e32 v203, v203, v202
	v_add_f32_e32 v249, v201, v203
	ds_bpermute_b32 v168, v0, v242
	ds_bpermute_b32 v169, v0, v243
	ds_bpermute_b32 v170, v0, v244
	ds_bpermute_b32 v171, v0, v245
	ds_bpermute_b32 v172, v0, v246
	ds_bpermute_b32 v173, v0, v247
	ds_bpermute_b32 v174, v0, v248
	ds_bpermute_b32 v175, v0, v249
	s_waitcnt lgkmcnt(0)
	v_add_f32_e32 v242, v242, v168
	v_add_f32_e32 v243, v243, v169
	v_add_f32_e32 v244, v244, v170
	v_add_f32_e32 v245, v245, v171
	v_add_f32_e32 v246, v246, v172
	v_add_f32_e32 v247, v247, v173
	v_add_f32_e32 v248, v248, v174
	v_add_f32_e32 v249, v249, v175
	ds_bpermute_b32 v168, v251, v242
	ds_bpermute_b32 v169, v251, v243
	ds_bpermute_b32 v170, v251, v244
	ds_bpermute_b32 v171, v251, v245
	ds_bpermute_b32 v172, v251, v246
	ds_bpermute_b32 v173, v251, v247
	ds_bpermute_b32 v174, v251, v248
	ds_bpermute_b32 v175, v251, v249
	v_lshlrev_b32_e32 v201, 6, v194
	v_add_u32_e32 v202, 0x2000, v201
	s_waitcnt lgkmcnt(0)
	v_add_f32_e32 v242, v242, v168
	v_add_f32_e32 v243, v243, v169
	v_add_f32_e32 v244, v244, v170
	v_add_f32_e32 v245, v245, v171
	v_add_f32_e32 v246, v246, v172
	v_add_f32_e32 v247, v247, v173
	v_add_f32_e32 v248, v248, v174
	v_add_f32_e32 v249, v249, v175
	s_and_saveexec_b64 s[8:9], vcc
	global_store_dword v201, v242, s[6:7]
	global_store_dword v201, v243, s[6:7] offset:1024
	global_store_dword v201, v244, s[6:7] offset:2048
	global_store_dword v201, v245, s[6:7] offset:3072
	global_store_dword v202, v246, s[6:7]
	global_store_dword v202, v247, s[6:7] offset:1024
	global_store_dword v202, v248, s[6:7] offset:2048
	global_store_dword v202, v249, s[6:7] offset:3072
	s_or_b64 exec, exec, s[8:9]
	s_getreg_b32 s0, hwreg(HW_REG_XCC_ID, 0, 4)
	s_waitcnt vmcnt(0)
	s_waitcnt lgkmcnt(0)
	s_barrier
	s_mov_b64 s[6:7], exec
	v_readlane_b32 s8, v252, 4
	v_readlane_b32 s9, v252, 5
	s_and_b64 s[8:9], s[6:7], s[8:9]
	s_xor_b64 s[6:7], s[8:9], s[6:7]
	s_mov_b64 exec, s[8:9]
	s_cbranch_execz .LBB0_601
	v_readlane_b32 s8, v253, 9
	s_waitcnt vmcnt(0) expcnt(0) lgkmcnt(0)
	s_and_b32 s0, s0, 15
	v_mov_b32_e32 v0, s8
	ds_read_b32 v99, v0
	v_readlane_b32 s8, v253, 10
	s_waitcnt lgkmcnt(0)
	v_cmp_ne_u32_e32 vcc, 0, v99
	v_mov_b32_e32 v0, s8
	ds_read_b32 v98, v0
	s_cbranch_vccnz .LBB0_564
	s_mov_b32 s14, 1
	s_branch .LBB0_552

.LBB0_601:
	s_or_b64 exec, exec, s[6:7]
	s_mov_b64 s[84:85], s[62:63]
	s_mov_b64 s[80:81], s[60:61]
	s_mov_b64 s[74:75], s[58:59]
	s_mov_b64 s[28:29], s[56:57]
	s_mov_b64 s[14:15], s[54:55]
	s_mov_b64 s[10:11], s[52:53]
	v_readlane_b32 s6, v254, 27
	v_readlane_b32 s7, v254, 28
	v_readlane_b32 s8, v253, 38
	v_readlane_b32 s9, v253, 39
	v_readlane_b32 s48, v253, 56
	v_readlane_b32 s49, v253, 57
	v_readlane_b32 s50, v254, 8
	v_readlane_b32 s51, v254, 9
	v_readlane_b32 s100, v254, 6
	v_readlane_b32 s101, v254, 7
	s_waitcnt lgkmcnt(0)
	s_barrier
	v_bfe_u32 v201, v204, 4, 2
	v_lshlrev_b32_e32 v202, 2, v166
	v_lshlrev_b32_e32 v203, 6, v194
	v_lshl_add_u32 v203, v201, 4, v203
	v_add_u32_e32 v206, 0x2000, v203
	v_xor_b32_e32 v207, 16, v209
	v_xor_b32_e32 v250, 32, v209
	v_lshlrev_b32_e32 v207, 2, v207
	v_lshlrev_b32_e32 v250, 2, v250
	global_load_dwordx4 v[210:213], v203, s[22:23]
	global_load_dwordx4 v[214:217], v203, s[22:23] offset:1024
	global_load_dwordx4 v[218:221], v203, s[22:23] offset:2048
	global_load_dwordx4 v[222:225], v203, s[22:23] offset:3072
	global_load_dwordx4 v[226:229], v206, s[22:23]
	global_load_dwordx4 v[230:233], v206, s[22:23] offset:1024
	global_load_dwordx4 v[234:237], v206, s[22:23] offset:2048
	global_load_dwordx4 v[238:241], v206, s[22:23] offset:3072
	global_load_dwordx4 v[122:125], v202, s[6:7]
	global_load_dwordx4 v[118:121], v202, s[6:7] offset:16
	global_load_dwordx4 v[110:113], v202, s[6:7] offset:512
	global_load_dwordx4 v[106:109], v202, s[6:7] offset:528
	s_and_b64 vcc, exec, s[8:9]
	s_cbranch_vccz .Lrn_g2_done
	global_load_dwordx4 v[114:117], v202, s[48:49]
	global_load_dwordx4 v[126:129], v202, s[48:49] offset:16
	global_load_dwordx4 v[98:101], v202, s[48:49] offset:512
	global_load_dwordx4 v[102:105], v202, s[48:49] offset:528
.Lrn_g2_done:
	v_lshlrev_b32_e32 v200, 12, v194
	v_lshl_add_u32 v200, v166, 2, v200
	v_lshlrev_b32_e32 v251, 11, v194
	v_lshl_add_u32 v251, v166, 1, v251
	v_readlane_b32 s6, v254, 10
	v_readlane_b32 s7, v254, 11
	s_waitcnt vmcnt(0)
	v_add_f32_e32 v210, v210, v211
	v_add_f32_e32 v212, v212, v213
	v_add_f32_e32 v242, v210, v212
	v_add_f32_e32 v214, v214, v215
	v_add_f32_e32 v216, v216, v217
	v_add_f32_e32 v243, v214, v216
	v_add_f32_e32 v218, v218, v219
	v_add_f32_e32 v220, v220, v221
	v_add_f32_e32 v244, v218, v220
	v_add_f32_e32 v222, v222, v223
	v_add_f32_e32 v224, v224, v225
	v_add_f32_e32 v245, v222, v224
	v_add_f32_e32 v226, v226, v227
	v_add_f32_e32 v228, v228, v229
	v_add_f32_e32 v246, v226, v228
	v_add_f32_e32 v230, v230, v231
	v_add_f32_e32 v232, v232, v233
	v_add_f32_e32 v247, v230, v232
	v_add_f32_e32 v234, v234, v235
	v_add_f32_e32 v236, v236, v237
	v_add_f32_e32 v248, v234, v236
	v_add_f32_e32 v238, v238, v239
	v_add_f32_e32 v240, v240, v241
	v_add_f32_e32 v249, v238, v240
	ds_bpermute_b32 v168, v207, v242
	ds_bpermute_b32 v169, v207, v243
	ds_bpermute_b32 v170, v207, v244
	ds_bpermute_b32 v171, v207, v245
	ds_bpermute_b32 v172, v207, v246
	ds_bpermute_b32 v173, v207, v247
	ds_bpermute_b32 v174, v207, v248
	ds_bpermute_b32 v175, v207, v249
	s_waitcnt lgkmcnt(0)
	v_add_f32_e32 v242, v242, v168
	v_add_f32_e32 v243, v243, v169
	v_add_f32_e32 v244, v244, v170
	v_add_f32_e32 v245, v245, v171
	v_add_f32_e32 v246, v246, v172
	v_add_f32_e32 v247, v247, v173
	v_add_f32_e32 v248, v248, v174
	v_add_f32_e32 v249, v249, v175
	ds_bpermute_b32 v168, v250, v242
	ds_bpermute_b32 v169, v250, v243
	ds_bpermute_b32 v170, v250, v244
	ds_bpermute_b32 v171, v250, v245
	ds_bpermute_b32 v172, v250, v246
	ds_bpermute_b32 v173, v250, v247
	ds_bpermute_b32 v174, v250, v248
	ds_bpermute_b32 v175, v250, v249
	s_waitcnt lgkmcnt(0)
	v_add_f32_e32 v242, v242, v168
	v_add_f32_e32 v243, v243, v169
	v_add_f32_e32 v244, v244, v170
	v_add_f32_e32 v245, v245, v171
	v_add_f32_e32 v246, v246, v172
	v_add_f32_e32 v247, v247, v173
	v_add_f32_e32 v248, v248, v174
	v_add_f32_e32 v249, v249, v175
	v_fmamk_f32 v242, v242, 0x3a800000, v205
	v_fmamk_f32 v243, v243, 0x3a800000, v205
	v_fmamk_f32 v244, v244, 0x3a800000, v205
	v_fmamk_f32 v245, v245, 0x3a800000, v205
	v_fmamk_f32 v246, v246, 0x3a800000, v205
	v_fmamk_f32 v247, v247, 0x3a800000, v205
	v_fmamk_f32 v248, v248, 0x3a800000, v205
	v_fmamk_f32 v249, v249, 0x3a800000, v205
	v_rsq_f32_e32 v242, v242
	v_rsq_f32_e32 v243, v243
	v_rsq_f32_e32 v244, v244
	v_rsq_f32_e32 v245, v245
	v_rsq_f32_e32 v246, v246
	v_rsq_f32_e32 v247, v247
	v_rsq_f32_e32 v248, v248
	v_rsq_f32_e32 v249, v249
	v_mov_b32_e32 v201, v200
	v_mov_b32_e32 v202, v251
	v_mov_b32_e32 v228, v242
	global_store_dwordx4 v201, v[150:153], s[100:101] nt
	global_store_dwordx4 v201, v[146:149], s[100:101] offset:16 nt
	global_store_dwordx4 v201, v[154:157], s[100:101] offset:512 nt
	global_store_dwordx4 v201, v[158:161], s[100:101] offset:528 nt
	v_pk_mul_f32 v[168:169], v[150:151], v[228:229] op_sel_hi:[1,0]
	v_pk_mul_f32 v[170:171], v[152:153], v[228:229] op_sel_hi:[1,0]
	v_pk_mul_f32 v[172:173], v[146:147], v[228:229] op_sel_hi:[1,0]
	v_pk_mul_f32 v[174:175], v[148:149], v[228:229] op_sel_hi:[1,0]
	v_pk_mul_f32 v[176:177], v[154:155], v[228:229] op_sel_hi:[1,0]
	v_pk_mul_f32 v[178:179], v[156:157], v[228:229] op_sel_hi:[1,0]
	v_pk_mul_f32 v[180:181], v[158:159], v[228:229] op_sel_hi:[1,0]
	v_pk_mul_f32 v[182:183], v[160:161], v[228:229] op_sel_hi:[1,0]
	v_pk_mul_f32 v[184:185], v[122:123], v[168:169]
	v_pk_mul_f32 v[186:187], v[124:125], v[170:171]
	v_pk_mul_f32 v[188:189], v[118:119], v[172:173]
	v_pk_mul_f32 v[190:191], v[120:121], v[174:175]
	v_pk_mul_f32 v[192:193], v[110:111], v[176:177]
	v_pk_mul_f32 v[194:195], v[112:113], v[178:179]
	v_pk_mul_f32 v[196:197], v[106:107], v[180:181]
	v_pk_mul_f32 v[198:199], v[108:109], v[182:183]
	v_cvt_pk_bf16_f32 v184, v184, v185
	v_cvt_pk_bf16_f32 v185, v186, v187
	v_cvt_pk_bf16_f32 v186, v188, v189
	v_cvt_pk_bf16_f32 v187, v190, v191
	global_store_dwordx4 v202, v[184:187], s[50:51]
	v_cvt_pk_bf16_f32 v192, v192, v193
	v_cvt_pk_bf16_f32 v193, v194, v195
	v_cvt_pk_bf16_f32 v194, v196, v197
	v_cvt_pk_bf16_f32 v195, v198, v199
	global_store_dwordx4 v202, v[192:195], s[50:51] offset:256
	s_and_b64 vcc, exec, s[8:9]
	s_cbranch_vccz .Lrn_nodual_0
	v_pk_mul_f32 v[210:211], v[114:115], v[168:169]
	v_pk_mul_f32 v[212:213], v[116:117], v[170:171]
	v_pk_mul_f32 v[214:215], v[126:127], v[172:173]
	v_pk_mul_f32 v[216:217], v[128:129], v[174:175]
	v_pk_mul_f32 v[218:219], v[98:99], v[176:177]
	v_pk_mul_f32 v[220:221], v[100:101], v[178:179]
	v_pk_mul_f32 v[222:223], v[102:103], v[180:181]
	v_pk_mul_f32 v[224:225], v[104:105], v[182:183]
	v_cvt_pk_bf16_f32 v210, v210, v211
	v_cvt_pk_bf16_f32 v211, v212, v213
	v_cvt_pk_bf16_f32 v212, v214, v215
	v_cvt_pk_bf16_f32 v213, v216, v217
	global_store_dwordx4 v202, v[210:213], s[6:7]
	v_cvt_pk_bf16_f32 v218, v218, v219
	v_cvt_pk_bf16_f32 v219, v220, v221
	v_cvt_pk_bf16_f32 v220, v222, v223
	v_cvt_pk_bf16_f32 v221, v224, v225
	global_store_dwordx4 v202, v[218:221], s[6:7] offset:256
.Lrn_nodual_0:
	v_add_u32_e32 v201, 0x10000, v200
	v_add_u32_e32 v202, 0x8000, v251
	v_mov_b32_e32 v228, v243
	global_store_dwordx4 v201, v[134:137], s[100:101] nt
	global_store_dwordx4 v201, v[130:133], s[100:101] offset:16 nt
	global_store_dwordx4 v201, v[138:141], s[100:101] offset:512 nt
	global_store_dwordx4 v201, v[142:145], s[100:101] offset:528 nt
	v_pk_mul_f32 v[168:169], v[134:135], v[228:229] op_sel_hi:[1,0]
	v_pk_mul_f32 v[170:171], v[136:137], v[228:229] op_sel_hi:[1,0]
	v_pk_mul_f32 v[172:173], v[130:131], v[228:229] op_sel_hi:[1,0]
	v_pk_mul_f32 v[174:175], v[132:133], v[228:229] op_sel_hi:[1,0]
	v_pk_mul_f32 v[176:177], v[138:139], v[228:229] op_sel_hi:[1,0]
	v_pk_mul_f32 v[178:179], v[140:141], v[228:229] op_sel_hi:[1,0]
	v_pk_mul_f32 v[180:181], v[142:143], v[228:229] op_sel_hi:[1,0]
	v_pk_mul_f32 v[182:183], v[144:145], v[228:229] op_sel_hi:[1,0]
	v_pk_mul_f32 v[184:185], v[122:123], v[168:169]
	v_pk_mul_f32 v[186:187], v[124:125], v[170:171]
	v_pk_mul_f32 v[188:189], v[118:119], v[172:173]
	v_pk_mul_f32 v[190:191], v[120:121], v[174:175]
	v_pk_mul_f32 v[192:193], v[110:111], v[176:177]
	v_pk_mul_f32 v[194:195], v[112:113], v[178:179]
	v_pk_mul_f32 v[196:197], v[106:107], v[180:181]
	v_pk_mul_f32 v[198:199], v[108:109], v[182:183]
	v_cvt_pk_bf16_f32 v184, v184, v185
	v_cvt_pk_bf16_f32 v185, v186, v187
	v_cvt_pk_bf16_f32 v186, v188, v189
	v_cvt_pk_bf16_f32 v187, v190, v191
	global_store_dwordx4 v202, v[184:187], s[50:51]
	v_cvt_pk_bf16_f32 v192, v192, v193
	v_cvt_pk_bf16_f32 v193, v194, v195
	v_cvt_pk_bf16_f32 v194, v196, v197
	v_cvt_pk_bf16_f32 v195, v198, v199
	global_store_dwordx4 v202, v[192:195], s[50:51] offset:256
	s_and_b64 vcc, exec, s[8:9]
	s_cbranch_vccz .Lrn_nodual_1
	v_pk_mul_f32 v[210:211], v[114:115], v[168:169]
	v_pk_mul_f32 v[212:213], v[116:117], v[170:171]
	v_pk_mul_f32 v[214:215], v[126:127], v[172:173]
	v_pk_mul_f32 v[216:217], v[128:129], v[174:175]
	v_pk_mul_f32 v[218:219], v[98:99], v[176:177]
	v_pk_mul_f32 v[220:221], v[100:101], v[178:179]
	v_pk_mul_f32 v[222:223], v[102:103], v[180:181]
	v_pk_mul_f32 v[224:225], v[104:105], v[182:183]
	v_cvt_pk_bf16_f32 v210, v210, v211
	v_cvt_pk_bf16_f32 v211, v212, v213
	v_cvt_pk_bf16_f32 v212, v214, v215
	v_cvt_pk_bf16_f32 v213, v216, v217
	global_store_dwordx4 v202, v[210:213], s[6:7]
	v_cvt_pk_bf16_f32 v218, v218, v219
	v_cvt_pk_bf16_f32 v219, v220, v221
	v_cvt_pk_bf16_f32 v220, v222, v223
	v_cvt_pk_bf16_f32 v221, v224, v225
	global_store_dwordx4 v202, v[218:221], s[6:7] offset:256
.Lrn_nodual_1:
	v_add_u32_e32 v201, 0x20000, v200
	v_add_u32_e32 v202, 0x10000, v251
	v_mov_b32_e32 v228, v244
	global_store_dwordx4 v201, v[86:89], s[100:101] nt
	global_store_dwordx4 v201, v[82:85], s[100:101] offset:16 nt
	global_store_dwordx4 v201, v[90:93], s[100:101] offset:512 nt
	global_store_dwordx4 v201, v[94:97], s[100:101] offset:528 nt
	v_pk_mul_f32 v[168:169], v[86:87], v[228:229] op_sel_hi:[1,0]
	v_pk_mul_f32 v[170:171], v[88:89], v[228:229] op_sel_hi:[1,0]
	v_pk_mul_f32 v[172:173], v[82:83], v[228:229] op_sel_hi:[1,0]
	v_pk_mul_f32 v[174:175], v[84:85], v[228:229] op_sel_hi:[1,0]
	v_pk_mul_f32 v[176:177], v[90:91], v[228:229] op_sel_hi:[1,0]
	v_pk_mul_f32 v[178:179], v[92:93], v[228:229] op_sel_hi:[1,0]
	v_pk_mul_f32 v[180:181], v[94:95], v[228:229] op_sel_hi:[1,0]
	v_pk_mul_f32 v[182:183], v[96:97], v[228:229] op_sel_hi:[1,0]
	v_pk_mul_f32 v[184:185], v[122:123], v[168:169]
	v_pk_mul_f32 v[186:187], v[124:125], v[170:171]
	v_pk_mul_f32 v[188:189], v[118:119], v[172:173]
	v_pk_mul_f32 v[190:191], v[120:121], v[174:175]
	v_pk_mul_f32 v[192:193], v[110:111], v[176:177]
	v_pk_mul_f32 v[194:195], v[112:113], v[178:179]
	v_pk_mul_f32 v[196:197], v[106:107], v[180:181]
	v_pk_mul_f32 v[198:199], v[108:109], v[182:183]
	v_cvt_pk_bf16_f32 v184, v184, v185
	v_cvt_pk_bf16_f32 v185, v186, v187
	v_cvt_pk_bf16_f32 v186, v188, v189
	v_cvt_pk_bf16_f32 v187, v190, v191
	global_store_dwordx4 v202, v[184:187], s[50:51]
	v_cvt_pk_bf16_f32 v192, v192, v193
	v_cvt_pk_bf16_f32 v193, v194, v195
	v_cvt_pk_bf16_f32 v194, v196, v197
	v_cvt_pk_bf16_f32 v195, v198, v199
	global_store_dwordx4 v202, v[192:195], s[50:51] offset:256
	s_and_b64 vcc, exec, s[8:9]
	s_cbranch_vccz .Lrn_nodual_2
	v_pk_mul_f32 v[210:211], v[114:115], v[168:169]
	v_pk_mul_f32 v[212:213], v[116:117], v[170:171]
	v_pk_mul_f32 v[214:215], v[126:127], v[172:173]
	v_pk_mul_f32 v[216:217], v[128:129], v[174:175]
	v_pk_mul_f32 v[218:219], v[98:99], v[176:177]
	v_pk_mul_f32 v[220:221], v[100:101], v[178:179]
	v_pk_mul_f32 v[222:223], v[102:103], v[180:181]
	v_pk_mul_f32 v[224:225], v[104:105], v[182:183]
	v_cvt_pk_bf16_f32 v210, v210, v211
	v_cvt_pk_bf16_f32 v211, v212, v213
	v_cvt_pk_bf16_f32 v212, v214, v215
	v_cvt_pk_bf16_f32 v213, v216, v217
	global_store_dwordx4 v202, v[210:213], s[6:7]
	v_cvt_pk_bf16_f32 v218, v218, v219
	v_cvt_pk_bf16_f32 v219, v220, v221
	v_cvt_pk_bf16_f32 v220, v222, v223
	v_cvt_pk_bf16_f32 v221, v224, v225
	global_store_dwordx4 v202, v[218:221], s[6:7] offset:256
.Lrn_nodual_2:
	v_add_u32_e32 v201, 0x30000, v200
	v_add_u32_e32 v202, 0x18000, v251
	v_mov_b32_e32 v228, v245
	global_store_dwordx4 v201, v[70:73], s[100:101] nt
	global_store_dwordx4 v201, v[66:69], s[100:101] offset:16 nt
	global_store_dwordx4 v201, v[74:77], s[100:101] offset:512 nt
	global_store_dwordx4 v201, v[78:81], s[100:101] offset:528 nt
	v_pk_mul_f32 v[168:169], v[70:71], v[228:229] op_sel_hi:[1,0]
	v_pk_mul_f32 v[170:171], v[72:73], v[228:229] op_sel_hi:[1,0]
	v_pk_mul_f32 v[172:173], v[66:67], v[228:229] op_sel_hi:[1,0]
	v_pk_mul_f32 v[174:175], v[68:69], v[228:229] op_sel_hi:[1,0]
	v_pk_mul_f32 v[176:177], v[74:75], v[228:229] op_sel_hi:[1,0]
	v_pk_mul_f32 v[178:179], v[76:77], v[228:229] op_sel_hi:[1,0]
	v_pk_mul_f32 v[180:181], v[78:79], v[228:229] op_sel_hi:[1,0]
	v_pk_mul_f32 v[182:183], v[80:81], v[228:229] op_sel_hi:[1,0]
	v_pk_mul_f32 v[184:185], v[122:123], v[168:169]
	v_pk_mul_f32 v[186:187], v[124:125], v[170:171]
	v_pk_mul_f32 v[188:189], v[118:119], v[172:173]
	v_pk_mul_f32 v[190:191], v[120:121], v[174:175]
	v_pk_mul_f32 v[192:193], v[110:111], v[176:177]
	v_pk_mul_f32 v[194:195], v[112:113], v[178:179]
	v_pk_mul_f32 v[196:197], v[106:107], v[180:181]
	v_pk_mul_f32 v[198:199], v[108:109], v[182:183]
	v_cvt_pk_bf16_f32 v184, v184, v185
	v_cvt_pk_bf16_f32 v185, v186, v187
	v_cvt_pk_bf16_f32 v186, v188, v189
	v_cvt_pk_bf16_f32 v187, v190, v191
	global_store_dwordx4 v202, v[184:187], s[50:51]
	v_cvt_pk_bf16_f32 v192, v192, v193
	v_cvt_pk_bf16_f32 v193, v194, v195
	v_cvt_pk_bf16_f32 v194, v196, v197
	v_cvt_pk_bf16_f32 v195, v198, v199
	global_store_dwordx4 v202, v[192:195], s[50:51] offset:256
	s_and_b64 vcc, exec, s[8:9]
	s_cbranch_vccz .Lrn_nodual_3
	v_pk_mul_f32 v[210:211], v[114:115], v[168:169]
	v_pk_mul_f32 v[212:213], v[116:117], v[170:171]
	v_pk_mul_f32 v[214:215], v[126:127], v[172:173]
	v_pk_mul_f32 v[216:217], v[128:129], v[174:175]
	v_pk_mul_f32 v[218:219], v[98:99], v[176:177]
	v_pk_mul_f32 v[220:221], v[100:101], v[178:179]
	v_pk_mul_f32 v[222:223], v[102:103], v[180:181]
	v_pk_mul_f32 v[224:225], v[104:105], v[182:183]
	v_cvt_pk_bf16_f32 v210, v210, v211
	v_cvt_pk_bf16_f32 v211, v212, v213
	v_cvt_pk_bf16_f32 v212, v214, v215
	v_cvt_pk_bf16_f32 v213, v216, v217
	global_store_dwordx4 v202, v[210:213], s[6:7]
	v_cvt_pk_bf16_f32 v218, v218, v219
	v_cvt_pk_bf16_f32 v219, v220, v221
	v_cvt_pk_bf16_f32 v220, v222, v223
	v_cvt_pk_bf16_f32 v221, v224, v225
	global_store_dwordx4 v202, v[218:221], s[6:7] offset:256
.Lrn_nodual_3:
	v_add_u32_e32 v201, 0x80000, v200
	v_add_u32_e32 v202, 0x40000, v251
	v_mov_b32_e32 v228, v246
	global_store_dwordx4 v201, v[54:57], s[100:101] nt
	global_store_dwordx4 v201, v[50:53], s[100:101] offset:16 nt
	global_store_dwordx4 v201, v[58:61], s[100:101] offset:512 nt
	global_store_dwordx4 v201, v[62:65], s[100:101] offset:528 nt
	v_pk_mul_f32 v[168:169], v[54:55], v[228:229] op_sel_hi:[1,0]
	v_pk_mul_f32 v[170:171], v[56:57], v[228:229] op_sel_hi:[1,0]
	v_pk_mul_f32 v[172:173], v[50:51], v[228:229] op_sel_hi:[1,0]
	v_pk_mul_f32 v[174:175], v[52:53], v[228:229] op_sel_hi:[1,0]
	v_pk_mul_f32 v[176:177], v[58:59], v[228:229] op_sel_hi:[1,0]
	v_pk_mul_f32 v[178:179], v[60:61], v[228:229] op_sel_hi:[1,0]
	v_pk_mul_f32 v[180:181], v[62:63], v[228:229] op_sel_hi:[1,0]
	v_pk_mul_f32 v[182:183], v[64:65], v[228:229] op_sel_hi:[1,0]
	v_pk_mul_f32 v[184:185], v[122:123], v[168:169]
	v_pk_mul_f32 v[186:187], v[124:125], v[170:171]
	v_pk_mul_f32 v[188:189], v[118:119], v[172:173]
	v_pk_mul_f32 v[190:191], v[120:121], v[174:175]
	v_pk_mul_f32 v[192:193], v[110:111], v[176:177]
	v_pk_mul_f32 v[194:195], v[112:113], v[178:179]
	v_pk_mul_f32 v[196:197], v[106:107], v[180:181]
	v_pk_mul_f32 v[198:199], v[108:109], v[182:183]
	v_cvt_pk_bf16_f32 v184, v184, v185
	v_cvt_pk_bf16_f32 v185, v186, v187
	v_cvt_pk_bf16_f32 v186, v188, v189
	v_cvt_pk_bf16_f32 v187, v190, v191
	global_store_dwordx4 v202, v[184:187], s[50:51]
	v_cvt_pk_bf16_f32 v192, v192, v193
	v_cvt_pk_bf16_f32 v193, v194, v195
	v_cvt_pk_bf16_f32 v194, v196, v197
	v_cvt_pk_bf16_f32 v195, v198, v199
	global_store_dwordx4 v202, v[192:195], s[50:51] offset:256
	s_and_b64 vcc, exec, s[8:9]
	s_cbranch_vccz .Lrn_nodual_4
	v_pk_mul_f32 v[210:211], v[114:115], v[168:169]
	v_pk_mul_f32 v[212:213], v[116:117], v[170:171]
	v_pk_mul_f32 v[214:215], v[126:127], v[172:173]
	v_pk_mul_f32 v[216:217], v[128:129], v[174:175]
	v_pk_mul_f32 v[218:219], v[98:99], v[176:177]
	v_pk_mul_f32 v[220:221], v[100:101], v[178:179]
	v_pk_mul_f32 v[222:223], v[102:103], v[180:181]
	v_pk_mul_f32 v[224:225], v[104:105], v[182:183]
	v_cvt_pk_bf16_f32 v210, v210, v211
	v_cvt_pk_bf16_f32 v211, v212, v213
	v_cvt_pk_bf16_f32 v212, v214, v215
	v_cvt_pk_bf16_f32 v213, v216, v217
	global_store_dwordx4 v202, v[210:213], s[6:7]
	v_cvt_pk_bf16_f32 v218, v218, v219
	v_cvt_pk_bf16_f32 v219, v220, v221
	v_cvt_pk_bf16_f32 v220, v222, v223
	v_cvt_pk_bf16_f32 v221, v224, v225
	global_store_dwordx4 v202, v[218:221], s[6:7] offset:256
.Lrn_nodual_4:
	v_add_u32_e32 v201, 0x90000, v200
	v_add_u32_e32 v202, 0x48000, v251
	v_mov_b32_e32 v228, v247
	global_store_dwordx4 v201, v[38:41], s[100:101] nt
	global_store_dwordx4 v201, v[34:37], s[100:101] offset:16 nt
	global_store_dwordx4 v201, v[42:45], s[100:101] offset:512 nt
	global_store_dwordx4 v201, v[46:49], s[100:101] offset:528 nt
	v_pk_mul_f32 v[168:169], v[38:39], v[228:229] op_sel_hi:[1,0]
	v_pk_mul_f32 v[170:171], v[40:41], v[228:229] op_sel_hi:[1,0]
	v_pk_mul_f32 v[172:173], v[34:35], v[228:229] op_sel_hi:[1,0]
	v_pk_mul_f32 v[174:175], v[36:37], v[228:229] op_sel_hi:[1,0]
	v_pk_mul_f32 v[176:177], v[42:43], v[228:229] op_sel_hi:[1,0]
	v_pk_mul_f32 v[178:179], v[44:45], v[228:229] op_sel_hi:[1,0]
	v_pk_mul_f32 v[180:181], v[46:47], v[228:229] op_sel_hi:[1,0]
	v_pk_mul_f32 v[182:183], v[48:49], v[228:229] op_sel_hi:[1,0]
	v_pk_mul_f32 v[184:185], v[122:123], v[168:169]
	v_pk_mul_f32 v[186:187], v[124:125], v[170:171]
	v_pk_mul_f32 v[188:189], v[118:119], v[172:173]
	v_pk_mul_f32 v[190:191], v[120:121], v[174:175]
	v_pk_mul_f32 v[192:193], v[110:111], v[176:177]
	v_pk_mul_f32 v[194:195], v[112:113], v[178:179]
	v_pk_mul_f32 v[196:197], v[106:107], v[180:181]
	v_pk_mul_f32 v[198:199], v[108:109], v[182:183]
	v_cvt_pk_bf16_f32 v184, v184, v185
	v_cvt_pk_bf16_f32 v185, v186, v187
	v_cvt_pk_bf16_f32 v186, v188, v189
	v_cvt_pk_bf16_f32 v187, v190, v191
	global_store_dwordx4 v202, v[184:187], s[50:51]
	v_cvt_pk_bf16_f32 v192, v192, v193
	v_cvt_pk_bf16_f32 v193, v194, v195
	v_cvt_pk_bf16_f32 v194, v196, v197
	v_cvt_pk_bf16_f32 v195, v198, v199
	global_store_dwordx4 v202, v[192:195], s[50:51] offset:256
	s_and_b64 vcc, exec, s[8:9]
	s_cbranch_vccz .Lrn_nodual_5
	v_pk_mul_f32 v[210:211], v[114:115], v[168:169]
	v_pk_mul_f32 v[212:213], v[116:117], v[170:171]
	v_pk_mul_f32 v[214:215], v[126:127], v[172:173]
	v_pk_mul_f32 v[216:217], v[128:129], v[174:175]
	v_pk_mul_f32 v[218:219], v[98:99], v[176:177]
	v_pk_mul_f32 v[220:221], v[100:101], v[178:179]
	v_pk_mul_f32 v[222:223], v[102:103], v[180:181]
	v_pk_mul_f32 v[224:225], v[104:105], v[182:183]
	v_cvt_pk_bf16_f32 v210, v210, v211
	v_cvt_pk_bf16_f32 v211, v212, v213
	v_cvt_pk_bf16_f32 v212, v214, v215
	v_cvt_pk_bf16_f32 v213, v216, v217
	global_store_dwordx4 v202, v[210:213], s[6:7]
	v_cvt_pk_bf16_f32 v218, v218, v219
	v_cvt_pk_bf16_f32 v219, v220, v221
	v_cvt_pk_bf16_f32 v220, v222, v223
	v_cvt_pk_bf16_f32 v221, v224, v225
	global_store_dwordx4 v202, v[218:221], s[6:7] offset:256
.Lrn_nodual_5:
	v_add_u32_e32 v201, 0xa0000, v200
	v_add_u32_e32 v202, 0x50000, v251
	v_mov_b32_e32 v228, v248
	global_store_dwordx4 v201, v[22:25], s[100:101] nt
	global_store_dwordx4 v201, v[18:21], s[100:101] offset:16 nt
	global_store_dwordx4 v201, v[26:29], s[100:101] offset:512 nt
	global_store_dwordx4 v201, v[30:33], s[100:101] offset:528 nt
	v_pk_mul_f32 v[168:169], v[22:23], v[228:229] op_sel_hi:[1,0]
	v_pk_mul_f32 v[170:171], v[24:25], v[228:229] op_sel_hi:[1,0]
	v_pk_mul_f32 v[172:173], v[18:19], v[228:229] op_sel_hi:[1,0]
	v_pk_mul_f32 v[174:175], v[20:21], v[228:229] op_sel_hi:[1,0]
	v_pk_mul_f32 v[176:177], v[26:27], v[228:229] op_sel_hi:[1,0]
	v_pk_mul_f32 v[178:179], v[28:29], v[228:229] op_sel_hi:[1,0]
	v_pk_mul_f32 v[180:181], v[30:31], v[228:229] op_sel_hi:[1,0]
	v_pk_mul_f32 v[182:183], v[32:33], v[228:229] op_sel_hi:[1,0]
	v_pk_mul_f32 v[184:185], v[122:123], v[168:169]
	v_pk_mul_f32 v[186:187], v[124:125], v[170:171]
	v_pk_mul_f32 v[188:189], v[118:119], v[172:173]
	v_pk_mul_f32 v[190:191], v[120:121], v[174:175]
	v_pk_mul_f32 v[192:193], v[110:111], v[176:177]
	v_pk_mul_f32 v[194:195], v[112:113], v[178:179]
	v_pk_mul_f32 v[196:197], v[106:107], v[180:181]
	v_pk_mul_f32 v[198:199], v[108:109], v[182:183]
	v_cvt_pk_bf16_f32 v184, v184, v185
	v_cvt_pk_bf16_f32 v185, v186, v187
	v_cvt_pk_bf16_f32 v186, v188, v189
	v_cvt_pk_bf16_f32 v187, v190, v191
	global_store_dwordx4 v202, v[184:187], s[50:51]
	v_cvt_pk_bf16_f32 v192, v192, v193
	v_cvt_pk_bf16_f32 v193, v194, v195
	v_cvt_pk_bf16_f32 v194, v196, v197
	v_cvt_pk_bf16_f32 v195, v198, v199
	global_store_dwordx4 v202, v[192:195], s[50:51] offset:256
	s_and_b64 vcc, exec, s[8:9]
	s_cbranch_vccz .Lrn_nodual_6
	v_pk_mul_f32 v[210:211], v[114:115], v[168:169]
	v_pk_mul_f32 v[212:213], v[116:117], v[170:171]
	v_pk_mul_f32 v[214:215], v[126:127], v[172:173]
	v_pk_mul_f32 v[216:217], v[128:129], v[174:175]
	v_pk_mul_f32 v[218:219], v[98:99], v[176:177]
	v_pk_mul_f32 v[220:221], v[100:101], v[178:179]
	v_pk_mul_f32 v[222:223], v[102:103], v[180:181]
	v_pk_mul_f32 v[224:225], v[104:105], v[182:183]
	v_cvt_pk_bf16_f32 v210, v210, v211
	v_cvt_pk_bf16_f32 v211, v212, v213
	v_cvt_pk_bf16_f32 v212, v214, v215
	v_cvt_pk_bf16_f32 v213, v216, v217
	global_store_dwordx4 v202, v[210:213], s[6:7]
	v_cvt_pk_bf16_f32 v218, v218, v219
	v_cvt_pk_bf16_f32 v219, v220, v221
	v_cvt_pk_bf16_f32 v220, v222, v223
	v_cvt_pk_bf16_f32 v221, v224, v225
	global_store_dwordx4 v202, v[218:221], s[6:7] offset:256
.Lrn_nodual_6:
	v_add_u32_e32 v201, 0xb0000, v200
	v_add_u32_e32 v202, 0x58000, v251
	v_mov_b32_e32 v228, v249
	global_store_dwordx4 v201, v[6:9], s[100:101] nt
	global_store_dwordx4 v201, v[2:5], s[100:101] offset:16 nt
	global_store_dwordx4 v201, v[10:13], s[100:101] offset:512 nt
	global_store_dwordx4 v201, v[14:17], s[100:101] offset:528 nt
	v_pk_mul_f32 v[168:169], v[6:7], v[228:229] op_sel_hi:[1,0]
	v_pk_mul_f32 v[170:171], v[8:9], v[228:229] op_sel_hi:[1,0]
	v_pk_mul_f32 v[172:173], v[2:3], v[228:229] op_sel_hi:[1,0]
	v_pk_mul_f32 v[174:175], v[4:5], v[228:229] op_sel_hi:[1,0]
	v_pk_mul_f32 v[176:177], v[10:11], v[228:229] op_sel_hi:[1,0]
	v_pk_mul_f32 v[178:179], v[12:13], v[228:229] op_sel_hi:[1,0]
	v_pk_mul_f32 v[180:181], v[14:15], v[228:229] op_sel_hi:[1,0]
	v_pk_mul_f32 v[182:183], v[16:17], v[228:229] op_sel_hi:[1,0]
	v_pk_mul_f32 v[184:185], v[122:123], v[168:169]
	v_pk_mul_f32 v[186:187], v[124:125], v[170:171]
	v_pk_mul_f32 v[188:189], v[118:119], v[172:173]
	v_pk_mul_f32 v[190:191], v[120:121], v[174:175]
	v_pk_mul_f32 v[192:193], v[110:111], v[176:177]
	v_pk_mul_f32 v[194:195], v[112:113], v[178:179]
	v_pk_mul_f32 v[196:197], v[106:107], v[180:181]
	v_pk_mul_f32 v[198:199], v[108:109], v[182:183]
	v_cvt_pk_bf16_f32 v184, v184, v185
	v_cvt_pk_bf16_f32 v185, v186, v187
	v_cvt_pk_bf16_f32 v186, v188, v189
	v_cvt_pk_bf16_f32 v187, v190, v191
	global_store_dwordx4 v202, v[184:187], s[50:51]
	v_cvt_pk_bf16_f32 v192, v192, v193
	v_cvt_pk_bf16_f32 v193, v194, v195
	v_cvt_pk_bf16_f32 v194, v196, v197
	v_cvt_pk_bf16_f32 v195, v198, v199
	global_store_dwordx4 v202, v[192:195], s[50:51] offset:256
	s_and_b64 vcc, exec, s[8:9]
	s_cbranch_vccz .Lrn_nodual_7
	v_pk_mul_f32 v[210:211], v[114:115], v[168:169]
	v_pk_mul_f32 v[212:213], v[116:117], v[170:171]
	v_pk_mul_f32 v[214:215], v[126:127], v[172:173]
	v_pk_mul_f32 v[216:217], v[128:129], v[174:175]
	v_pk_mul_f32 v[218:219], v[98:99], v[176:177]
	v_pk_mul_f32 v[220:221], v[100:101], v[178:179]
	v_pk_mul_f32 v[222:223], v[102:103], v[180:181]
	v_pk_mul_f32 v[224:225], v[104:105], v[182:183]
	v_cvt_pk_bf16_f32 v210, v210, v211
	v_cvt_pk_bf16_f32 v211, v212, v213
	v_cvt_pk_bf16_f32 v212, v214, v215
	v_cvt_pk_bf16_f32 v213, v216, v217
	global_store_dwordx4 v202, v[210:213], s[6:7]
	v_cvt_pk_bf16_f32 v218, v218, v219
	v_cvt_pk_bf16_f32 v219, v220, v221
	v_cvt_pk_bf16_f32 v220, v222, v223
	v_cvt_pk_bf16_f32 v221, v224, v225
	global_store_dwordx4 v202, v[218:221], s[6:7] offset:256
.Lrn_nodual_7:
	s_mov_b64 s[52:53], s[10:11]
	s_mov_b64 s[54:55], s[14:15]
	s_mov_b64 s[56:57], s[28:29]
	s_mov_b64 s[58:59], s[74:75]
	s_mov_b64 s[60:61], s[80:81]
	s_mov_b64 s[62:63], s[84:85]
	v_readlane_b32 s48, v253, 56
	v_readlane_b32 s49, v253, 57
	v_readlane_b32 s50, v253, 58
	v_readlane_b32 s51, v253, 59
	v_readlane_b32 s8, v254, 39
	v_readlane_b32 s9, v254, 40
	s_branch .LBB0_509
